# down-GEMM epilogue rewritten: residual-base loads hoisted + coalesced via per-wave LDS stage, f32 stores coalesced; grid-barrier L1 invalidate moved ahead of the spin
# speedup vs baseline: 1.0305x; 1.0179x over previous
.LBB0_313:
	s_or_b64 exec, exec, s[8:9]
	v_cvt_f32_u32_e32 v4, v2
	s_waitcnt vmcnt(0)
	v_readfirstlane_b32 s3, v3
	v_sub_u32_e32 v3, 0, v2
	v_rcp_iflag_f32_e32 v4, v4
	v_add_u32_e32 v5, s3, v1
	v_mul_f32_e32 v4, 0x4f7ffffe, v4
	v_cvt_u32_f32_e32 v4, v4
	v_mul_lo_u32 v1, v3, v4
	v_mul_hi_u32 v1, v4, v1
	v_add_u32_e32 v1, v4, v1
	v_mul_hi_u32 v1, v5, v1
	v_mul_lo_u32 v3, v1, v2
	v_sub_u32_e32 v3, v5, v3
	v_add_u32_e32 v4, 1, v1
	v_cmp_ge_u32_e32 vcc, v3, v2
	s_nop 1
	v_cndmask_b32_e32 v1, v1, v4, vcc
	v_sub_u32_e32 v4, v3, v2
	v_cndmask_b32_e32 v3, v3, v4, vcc
	v_add_u32_e32 v4, 1, v1
	v_cmp_ge_u32_e32 vcc, v3, v2
	v_add_u32_e32 v3, 1, v5
	s_nop 0
	v_cndmask_b32_e32 v1, v1, v4, vcc
	v_mul_lo_u32 v4, v2, v1
	v_add_u32_e32 v2, v4, v2
	v_cmp_ne_u32_e32 vcc, v3, v2
	s_and_saveexec_b64 s[6:7], vcc
	s_xor_b64 s[6:7], exec, s[6:7]
	s_cbranch_execz .LBB0_327
	s_waitcnt lgkmcnt(0)
	buffer_inv sc1
	v_mov_b32_e32 v0, 0x2000
	global_load_dword v0, v0, s[4:5] offset:1024 sc1
	s_add_u32 s12, s4, 0x2400
	s_addc_u32 s13, s5, 0
	s_waitcnt vmcnt(0)
	v_cmp_eq_u32_e32 vcc, v0, v1
	s_and_saveexec_b64 s[8:9], vcc
	s_cbranch_execz .LBB0_326
	s_add_u32 s10, s30, 0x4a0200
	s_addc_u32 s11, s31, 0
	s_mov_b32 s3, 1
	s_mov_b64 s[14:15], 0
	v_mov_b32_e32 v0, 0
	s_branch .LBB0_317

.LBB0_326:
	s_or_b64 exec, exec, s[8:9]
	s_waitcnt vmcnt(0)
	s_waitcnt vmcnt(0)

.LBB0_330:
	s_or_b64 exec, exec, s[8:9]
	v_cvt_f32_u32_e32 v3, v0
	s_waitcnt vmcnt(0)
	v_readfirstlane_b32 s3, v2
	s_add_u32 s8, s30, 0x4a3500
	s_addc_u32 s9, s31, 0
	v_rcp_iflag_f32_e32 v3, v3
	v_add_u32_e32 v1, s3, v1
	v_add_u32_e32 v4, 1, v1
	s_mov_b64 s[10:11], -1
	v_mul_f32_e32 v2, 0x4f7ffffe, v3
	v_cvt_u32_f32_e32 v2, v2
	v_sub_u32_e32 v3, 0, v0
	v_mul_lo_u32 v3, v3, v2
	v_mul_hi_u32 v3, v2, v3
	v_add_u32_e32 v2, v2, v3
	v_mul_hi_u32 v2, v1, v2
	v_mul_lo_u32 v3, v2, v0
	v_sub_u32_e32 v1, v1, v3
	v_add_u32_e32 v5, 1, v2
	v_cmp_ge_u32_e32 vcc, v1, v0
	v_sub_u32_e32 v3, v1, v0
	s_nop 0
	v_cndmask_b32_e32 v2, v2, v5, vcc
	v_cndmask_b32_e32 v1, v1, v3, vcc
	v_add_u32_e32 v3, 1, v2
	v_cmp_ge_u32_e32 vcc, v1, v0
	s_nop 1
	v_cndmask_b32_e32 v2, v2, v3, vcc
	v_mul_lo_u32 v1, v0, v2
	v_add_u32_e32 v0, v1, v0
	v_cmp_ne_u32_e32 vcc, v4, v0
	v_mov_b64_e32 v[0:1], s[8:9]
	s_and_saveexec_b64 s[6:7], vcc
	s_cbranch_execz .LBB0_342
	buffer_inv sc1
	v_mov_b32_e32 v0, 0
	global_load_dword v1, v0, s[8:9] sc1
	s_mov_b64 s[14:15], 0
	s_waitcnt vmcnt(0)
	v_cmp_eq_u32_e32 vcc, v1, v2
	s_and_saveexec_b64 s[12:13], vcc
	s_cbranch_execz .LBB0_341
	s_add_u32 s10, s30, 0x4a0200
	s_addc_u32 s11, s31, 0
	s_mov_b32 s3, 1
	s_branch .LBB0_334

.LBB0_342:
	s_or_b64 exec, exec, s[6:7]
	s_and_saveexec_b64 s[6:7], s[10:11]
	s_cbranch_execz .LBB0_344
	v_mov_b32_e32 v2, 1
	global_atomic_add v[0:1], v2, off
	buffer_inv sc1
.LBB0_344:
	s_or_b64 exec, exec, s[6:7]
	s_mov_b64 s[6:7], exec
	v_mbcnt_lo_u32_b32 v0, s6, 0
	v_mbcnt_hi_u32_b32 v0, s7, v0
	v_cmp_eq_u32_e32 vcc, 0, v0
	s_waitcnt vmcnt(0)
	s_and_saveexec_b64 s[8:9], vcc
	s_cbranch_execz .LBB0_346
	s_bcnt1_i32_b64 s3, s[6:7]
	v_mov_b32_e32 v0, 0x2000
	v_mov_b32_e32 v1, s3
	global_atomic_add v0, v1, s[4:5] offset:1024

.LBB0_459:
	s_or_b64 exec, exec, s[8:9]
	v_cvt_f32_u32_e32 v4, v2
	s_waitcnt vmcnt(0)
	v_readfirstlane_b32 s6, v3
	v_sub_u32_e32 v3, 0, v2
	v_rcp_iflag_f32_e32 v4, v4
	v_add_u32_e32 v5, s6, v1
	v_mul_f32_e32 v4, 0x4f7ffffe, v4
	v_cvt_u32_f32_e32 v4, v4
	v_mul_lo_u32 v1, v3, v4
	v_mul_hi_u32 v1, v4, v1
	v_add_u32_e32 v1, v4, v1
	v_mul_hi_u32 v1, v5, v1
	v_mul_lo_u32 v3, v1, v2
	v_sub_u32_e32 v3, v5, v3
	v_add_u32_e32 v4, 1, v1
	v_cmp_ge_u32_e32 vcc, v3, v2
	s_nop 1
	v_cndmask_b32_e32 v1, v1, v4, vcc
	v_sub_u32_e32 v4, v3, v2
	v_cndmask_b32_e32 v3, v3, v4, vcc
	v_add_u32_e32 v4, 1, v1
	v_cmp_ge_u32_e32 vcc, v3, v2
	v_add_u32_e32 v3, 1, v5
	s_nop 0
	v_cndmask_b32_e32 v1, v1, v4, vcc
	v_mul_lo_u32 v4, v2, v1
	v_add_u32_e32 v2, v4, v2
	v_cmp_ne_u32_e32 vcc, v3, v2
	s_and_saveexec_b64 s[6:7], vcc
	s_xor_b64 s[6:7], exec, s[6:7]
	s_cbranch_execz .LBB0_473
	s_waitcnt lgkmcnt(0)
	buffer_inv sc1
	v_mov_b32_e32 v0, 0x2000
	global_load_dword v0, v0, s[4:5] offset:1024 sc1
	s_add_u32 s16, s4, 0x2400
	s_addc_u32 s17, s5, 0
	s_waitcnt vmcnt(0)
	v_cmp_eq_u32_e32 vcc, v0, v1
	s_and_saveexec_b64 s[8:9], vcc
	s_cbranch_execz .LBB0_472
	s_add_u32 s10, s30, 0x4a0200
	s_addc_u32 s11, s31, 0
	s_mov_b32 s40, 1
	s_mov_b64 s[18:19], 0
	v_mov_b32_e32 v0, 0
	s_branch .LBB0_463

.LBB0_476:
	s_or_b64 exec, exec, s[8:9]
	v_cvt_f32_u32_e32 v3, v0
	s_waitcnt vmcnt(0)
	v_readfirstlane_b32 s6, v2
	s_add_u32 s8, s30, 0x4a3500
	s_addc_u32 s9, s31, 0
	v_rcp_iflag_f32_e32 v3, v3
	v_add_u32_e32 v1, s6, v1
	v_add_u32_e32 v4, 1, v1
	s_mov_b64 s[10:11], -1
	v_mul_f32_e32 v2, 0x4f7ffffe, v3
	v_cvt_u32_f32_e32 v2, v2
	v_sub_u32_e32 v3, 0, v0
	v_mul_lo_u32 v3, v3, v2
	v_mul_hi_u32 v3, v2, v3
	v_add_u32_e32 v2, v2, v3
	v_mul_hi_u32 v2, v1, v2
	v_mul_lo_u32 v3, v2, v0
	v_sub_u32_e32 v1, v1, v3
	v_add_u32_e32 v5, 1, v2
	v_cmp_ge_u32_e32 vcc, v1, v0
	v_sub_u32_e32 v3, v1, v0
	s_nop 0
	v_cndmask_b32_e32 v2, v2, v5, vcc
	v_cndmask_b32_e32 v1, v1, v3, vcc
	v_add_u32_e32 v3, 1, v2
	v_cmp_ge_u32_e32 vcc, v1, v0
	s_nop 1
	v_cndmask_b32_e32 v2, v2, v3, vcc
	v_mul_lo_u32 v1, v0, v2
	v_add_u32_e32 v0, v1, v0
	v_cmp_ne_u32_e32 vcc, v4, v0
	v_mov_b64_e32 v[0:1], s[8:9]
	s_and_saveexec_b64 s[6:7], vcc
	s_cbranch_execz .LBB0_488
	buffer_inv sc1
	v_mov_b32_e32 v0, 0
	global_load_dword v1, v0, s[8:9] sc1
	s_mov_b64 s[18:19], 0
	s_waitcnt vmcnt(0)
	v_cmp_eq_u32_e32 vcc, v1, v2
	s_and_saveexec_b64 s[16:17], vcc
	s_cbranch_execz .LBB0_487
	s_add_u32 s10, s30, 0x4a0200
	s_addc_u32 s11, s31, 0
	s_mov_b32 s40, 1
	s_branch .LBB0_480

.LBB0_490:
	s_or_b64 exec, exec, s[6:7]
	s_mov_b64 s[6:7], exec
	v_mbcnt_lo_u32_b32 v0, s6, 0
	v_mbcnt_hi_u32_b32 v0, s7, v0
	v_cmp_eq_u32_e32 vcc, 0, v0
	s_waitcnt vmcnt(0)
	s_and_saveexec_b64 s[8:9], vcc
	s_cbranch_execz .LBB0_492
	s_bcnt1_i32_b64 s6, s[6:7]
	v_mov_b32_e32 v0, 0x2000
	v_mov_b32_e32 v1, s6
	global_atomic_add v0, v1, s[4:5] offset:1024

.LBB0_582:
	s_or_b64 exec, exec, s[20:21]
	v_cvt_f32_u32_e32 v4, v2
	s_waitcnt vmcnt(0)
	v_readfirstlane_b32 s3, v3
	v_sub_u32_e32 v3, 0, v2
	v_rcp_iflag_f32_e32 v4, v4
	v_add_u32_e32 v5, s3, v1
	v_mul_f32_e32 v4, 0x4f7ffffe, v4
	v_cvt_u32_f32_e32 v4, v4
	v_mul_lo_u32 v1, v3, v4
	v_mul_hi_u32 v1, v4, v1
	v_add_u32_e32 v1, v4, v1
	v_mul_hi_u32 v1, v5, v1
	v_mul_lo_u32 v3, v1, v2
	v_sub_u32_e32 v3, v5, v3
	v_add_u32_e32 v4, 1, v1
	v_cmp_ge_u32_e32 vcc, v3, v2
	s_nop 1
	v_cndmask_b32_e32 v1, v1, v4, vcc
	v_sub_u32_e32 v4, v3, v2
	v_cndmask_b32_e32 v3, v3, v4, vcc
	v_add_u32_e32 v4, 1, v1
	v_cmp_ge_u32_e32 vcc, v3, v2
	v_add_u32_e32 v3, 1, v5
	s_nop 0
	v_cndmask_b32_e32 v1, v1, v4, vcc
	v_mul_lo_u32 v4, v2, v1
	v_add_u32_e32 v2, v4, v2
	v_cmp_ne_u32_e32 vcc, v3, v2
	s_and_saveexec_b64 s[6:7], vcc
	s_xor_b64 s[6:7], exec, s[6:7]
	s_cbranch_execz .LBB0_596
	s_waitcnt lgkmcnt(0)
	buffer_inv sc1
	v_mov_b32_e32 v0, 0x2000
	global_load_dword v0, v0, s[4:5] offset:1024 sc1
	s_add_u32 s24, s4, 0x2400
	s_addc_u32 s25, s5, 0
	s_waitcnt vmcnt(0)
	v_cmp_eq_u32_e32 vcc, v0, v1
	s_and_saveexec_b64 s[20:21], vcc
	s_cbranch_execz .LBB0_595
	s_add_u32 s22, s30, 0x4a0200
	s_addc_u32 s23, s31, 0
	s_mov_b32 s3, 1
	s_mov_b64 s[36:37], 0
	v_mov_b32_e32 v0, 0
	s_branch .LBB0_586

.LBB0_595:
	s_or_b64 exec, exec, s[20:21]
	s_waitcnt vmcnt(0)
	s_waitcnt vmcnt(0)

.LBB0_599:
	s_or_b64 exec, exec, s[20:21]
	v_cvt_f32_u32_e32 v3, v0
	s_waitcnt vmcnt(0)
	v_readfirstlane_b32 s3, v2
	s_add_u32 s20, s30, 0x4a3500
	s_addc_u32 s21, s31, 0
	v_rcp_iflag_f32_e32 v3, v3
	v_add_u32_e32 v1, s3, v1
	v_add_u32_e32 v4, 1, v1
	s_mov_b64 s[22:23], -1
	v_mul_f32_e32 v2, 0x4f7ffffe, v3
	v_cvt_u32_f32_e32 v2, v2
	v_sub_u32_e32 v3, 0, v0
	v_mul_lo_u32 v3, v3, v2
	v_mul_hi_u32 v3, v2, v3
	v_add_u32_e32 v2, v2, v3
	v_mul_hi_u32 v2, v1, v2
	v_mul_lo_u32 v3, v2, v0
	v_sub_u32_e32 v1, v1, v3
	v_add_u32_e32 v5, 1, v2
	v_cmp_ge_u32_e32 vcc, v1, v0
	v_sub_u32_e32 v3, v1, v0
	s_nop 0
	v_cndmask_b32_e32 v2, v2, v5, vcc
	v_cndmask_b32_e32 v1, v1, v3, vcc
	v_add_u32_e32 v3, 1, v2
	v_cmp_ge_u32_e32 vcc, v1, v0
	s_nop 1
	v_cndmask_b32_e32 v2, v2, v3, vcc
	v_mul_lo_u32 v1, v0, v2
	v_add_u32_e32 v0, v1, v0
	v_cmp_ne_u32_e32 vcc, v4, v0
	v_mov_b64_e32 v[0:1], s[20:21]
	s_and_saveexec_b64 s[6:7], vcc
	s_cbranch_execz .LBB0_611
	buffer_inv sc1
	v_mov_b32_e32 v0, 0
	global_load_dword v1, v0, s[20:21] sc1
	s_mov_b64 s[36:37], 0
	s_waitcnt vmcnt(0)
	v_cmp_eq_u32_e32 vcc, v1, v2
	s_and_saveexec_b64 s[24:25], vcc
	s_cbranch_execz .LBB0_610
	s_add_u32 s22, s30, 0x4a0200
	s_addc_u32 s23, s31, 0
	s_mov_b32 s3, 1
	s_branch .LBB0_603

.LBB0_611:
	s_or_b64 exec, exec, s[6:7]
	s_and_saveexec_b64 s[6:7], s[22:23]
	s_cbranch_execz .LBB0_613
	v_mov_b32_e32 v2, 1
	global_atomic_add v[0:1], v2, off
	buffer_inv sc1
.LBB0_613:
	s_or_b64 exec, exec, s[6:7]
	s_mov_b64 s[6:7], exec
	v_mbcnt_lo_u32_b32 v0, s6, 0
	v_mbcnt_hi_u32_b32 v0, s7, v0
	v_cmp_eq_u32_e32 vcc, 0, v0
	s_waitcnt vmcnt(0)
	s_and_saveexec_b64 s[20:21], vcc
	s_cbranch_execz .LBB0_615
	s_bcnt1_i32_b64 s3, s[6:7]
	v_mov_b32_e32 v0, 0x2000
	v_mov_b32_e32 v1, s3
	global_atomic_add v0, v1, s[4:5] offset:1024

.LBB0_676:
	s_or_b64 exec, exec, s[22:23]
	v_cvt_f32_u32_e32 v4, v2
	s_waitcnt vmcnt(0)
	v_readfirstlane_b32 s3, v3
	v_sub_u32_e32 v3, 0, v2
	v_rcp_iflag_f32_e32 v4, v4
	v_add_u32_e32 v5, s3, v1
	v_mul_f32_e32 v4, 0x4f7ffffe, v4
	v_cvt_u32_f32_e32 v4, v4
	v_mul_lo_u32 v1, v3, v4
	v_mul_hi_u32 v1, v4, v1
	v_add_u32_e32 v1, v4, v1
	v_mul_hi_u32 v1, v5, v1
	v_mul_lo_u32 v3, v1, v2
	v_sub_u32_e32 v3, v5, v3
	v_add_u32_e32 v4, 1, v1
	v_cmp_ge_u32_e32 vcc, v3, v2
	s_nop 1
	v_cndmask_b32_e32 v1, v1, v4, vcc
	v_sub_u32_e32 v4, v3, v2
	v_cndmask_b32_e32 v3, v3, v4, vcc
	v_add_u32_e32 v4, 1, v1
	v_cmp_ge_u32_e32 vcc, v3, v2
	v_add_u32_e32 v3, 1, v5
	s_nop 0
	v_cndmask_b32_e32 v1, v1, v4, vcc
	v_mul_lo_u32 v4, v2, v1
	v_add_u32_e32 v2, v4, v2
	v_cmp_ne_u32_e32 vcc, v3, v2
	s_and_saveexec_b64 s[20:21], vcc
	s_xor_b64 s[20:21], exec, s[20:21]
	s_cbranch_execz .LBB0_690
	s_waitcnt lgkmcnt(0)
	buffer_inv sc1
	v_mov_b32_e32 v0, 0x2000
	global_load_dword v0, v0, s[6:7] offset:1024 sc1
	s_add_u32 s36, s6, 0x2400
	s_addc_u32 s37, s7, 0
	s_waitcnt vmcnt(0)
	v_cmp_eq_u32_e32 vcc, v0, v1
	s_and_saveexec_b64 s[22:23], vcc
	s_cbranch_execz .LBB0_689
	s_add_u32 s24, s30, 0x4a0200
	s_addc_u32 s25, s31, 0
	s_mov_b32 s3, 1
	s_mov_b64 s[38:39], 0
	v_mov_b32_e32 v0, 0
	s_branch .LBB0_680

.LBB0_689:
	s_or_b64 exec, exec, s[22:23]
	s_waitcnt vmcnt(0)
	s_waitcnt vmcnt(0)

.LBB0_693:
	s_or_b64 exec, exec, s[22:23]
	v_cvt_f32_u32_e32 v3, v0
	s_waitcnt vmcnt(0)
	v_readfirstlane_b32 s3, v2
	s_add_u32 s22, s30, 0x4a3500
	s_addc_u32 s23, s31, 0
	v_rcp_iflag_f32_e32 v3, v3
	v_add_u32_e32 v1, s3, v1
	v_add_u32_e32 v4, 1, v1
	s_mov_b64 s[24:25], -1
	v_mul_f32_e32 v2, 0x4f7ffffe, v3
	v_cvt_u32_f32_e32 v2, v2
	v_sub_u32_e32 v3, 0, v0
	v_mul_lo_u32 v3, v3, v2
	v_mul_hi_u32 v3, v2, v3
	v_add_u32_e32 v2, v2, v3
	v_mul_hi_u32 v2, v1, v2
	v_mul_lo_u32 v3, v2, v0
	v_sub_u32_e32 v1, v1, v3
	v_add_u32_e32 v5, 1, v2
	v_cmp_ge_u32_e32 vcc, v1, v0
	v_sub_u32_e32 v3, v1, v0
	s_nop 0
	v_cndmask_b32_e32 v2, v2, v5, vcc
	v_cndmask_b32_e32 v1, v1, v3, vcc
	v_add_u32_e32 v3, 1, v2
	v_cmp_ge_u32_e32 vcc, v1, v0
	s_nop 1
	v_cndmask_b32_e32 v2, v2, v3, vcc
	v_mul_lo_u32 v1, v0, v2
	v_add_u32_e32 v0, v1, v0
	v_cmp_ne_u32_e32 vcc, v4, v0
	v_mov_b64_e32 v[0:1], s[22:23]
	s_and_saveexec_b64 s[20:21], vcc
	s_cbranch_execz .LBB0_705
	buffer_inv sc1
	v_mov_b32_e32 v0, 0
	global_load_dword v1, v0, s[22:23] sc1
	s_mov_b64 s[38:39], 0
	s_waitcnt vmcnt(0)
	v_cmp_eq_u32_e32 vcc, v1, v2
	s_and_saveexec_b64 s[36:37], vcc
	s_cbranch_execz .LBB0_704
	s_add_u32 s24, s30, 0x4a0200
	s_addc_u32 s25, s31, 0
	s_mov_b32 s3, 1
	s_branch .LBB0_697

.LBB0_705:
	s_or_b64 exec, exec, s[20:21]
	s_and_saveexec_b64 s[20:21], s[24:25]
	s_cbranch_execz .LBB0_707
	v_mov_b32_e32 v2, 1
	global_atomic_add v[0:1], v2, off
	buffer_inv sc1
.LBB0_707:
	s_or_b64 exec, exec, s[20:21]
	s_mov_b64 s[20:21], exec
	v_mbcnt_lo_u32_b32 v0, s20, 0
	v_mbcnt_hi_u32_b32 v0, s21, v0
	v_cmp_eq_u32_e32 vcc, 0, v0
	s_waitcnt vmcnt(0)
	s_and_saveexec_b64 s[22:23], vcc
	s_cbranch_execz .LBB0_709
	s_bcnt1_i32_b64 s3, s[20:21]
	v_mov_b32_e32 v0, 0x2000
	v_mov_b32_e32 v1, s3
	global_atomic_add v0, v1, s[6:7] offset:1024

.LBB0_782:
	s_or_b64 exec, exec, s[10:11]
	v_cvt_f32_u32_e32 v4, v2
	s_waitcnt vmcnt(0)
	v_readfirstlane_b32 s8, v3
	v_sub_u32_e32 v3, 0, v2
	v_rcp_iflag_f32_e32 v4, v4
	v_add_u32_e32 v5, s8, v1
	v_mul_f32_e32 v4, 0x4f7ffffe, v4
	v_cvt_u32_f32_e32 v4, v4
	v_mul_lo_u32 v1, v3, v4
	v_mul_hi_u32 v1, v4, v1
	v_add_u32_e32 v1, v4, v1
	v_mul_hi_u32 v1, v5, v1
	v_mul_lo_u32 v3, v1, v2
	v_sub_u32_e32 v3, v5, v3
	v_add_u32_e32 v4, 1, v1
	v_cmp_ge_u32_e32 vcc, v3, v2
	s_nop 1
	v_cndmask_b32_e32 v1, v1, v4, vcc
	v_sub_u32_e32 v4, v3, v2
	v_cndmask_b32_e32 v3, v3, v4, vcc
	v_add_u32_e32 v4, 1, v1
	v_cmp_ge_u32_e32 vcc, v3, v2
	v_add_u32_e32 v3, 1, v5
	s_nop 0
	v_cndmask_b32_e32 v1, v1, v4, vcc
	v_mul_lo_u32 v4, v2, v1
	v_add_u32_e32 v2, v4, v2
	v_cmp_ne_u32_e32 vcc, v3, v2
	s_and_saveexec_b64 s[8:9], vcc
	s_xor_b64 s[8:9], exec, s[8:9]
	s_cbranch_execz .LBB0_796
	s_waitcnt lgkmcnt(0)
	buffer_inv sc1
	v_mov_b32_e32 v0, 0x2000
	global_load_dword v0, v0, s[6:7] offset:1024 sc1
	s_add_u32 s22, s6, 0x2400
	s_addc_u32 s23, s7, 0
	s_waitcnt vmcnt(0)
	v_cmp_eq_u32_e32 vcc, v0, v1
	s_and_saveexec_b64 s[10:11], vcc
	s_cbranch_execz .LBB0_795
	s_add_u32 s18, s30, 0x4a0200
	s_addc_u32 s19, s31, 0
	s_mov_b32 s44, 1
	s_mov_b64 s[24:25], 0
	v_mov_b32_e32 v0, 0
	s_branch .LBB0_786

.LBB0_795:
	s_or_b64 exec, exec, s[10:11]
	s_waitcnt vmcnt(0)
	s_waitcnt vmcnt(0)

.LBB0_799:
	s_or_b64 exec, exec, s[10:11]
	v_cvt_f32_u32_e32 v3, v0
	s_waitcnt vmcnt(0)
	v_readfirstlane_b32 s8, v2
	s_add_u32 s10, s30, 0x4a3500
	s_addc_u32 s11, s31, 0
	v_rcp_iflag_f32_e32 v3, v3
	v_add_u32_e32 v1, s8, v1
	v_add_u32_e32 v4, 1, v1
	s_mov_b64 s[18:19], -1
	v_mul_f32_e32 v2, 0x4f7ffffe, v3
	v_cvt_u32_f32_e32 v2, v2
	v_sub_u32_e32 v3, 0, v0
	v_mul_lo_u32 v3, v3, v2
	v_mul_hi_u32 v3, v2, v3
	v_add_u32_e32 v2, v2, v3
	v_mul_hi_u32 v2, v1, v2
	v_mul_lo_u32 v3, v2, v0
	v_sub_u32_e32 v1, v1, v3
	v_add_u32_e32 v5, 1, v2
	v_cmp_ge_u32_e32 vcc, v1, v0
	v_sub_u32_e32 v3, v1, v0
	s_nop 0
	v_cndmask_b32_e32 v2, v2, v5, vcc
	v_cndmask_b32_e32 v1, v1, v3, vcc
	v_add_u32_e32 v3, 1, v2
	v_cmp_ge_u32_e32 vcc, v1, v0
	s_nop 1
	v_cndmask_b32_e32 v2, v2, v3, vcc
	v_mul_lo_u32 v1, v0, v2
	v_add_u32_e32 v0, v1, v0
	v_cmp_ne_u32_e32 vcc, v4, v0
	v_mov_b64_e32 v[0:1], s[10:11]
	s_and_saveexec_b64 s[8:9], vcc
	s_cbranch_execz .LBB0_811
	buffer_inv sc1
	v_mov_b32_e32 v0, 0
	global_load_dword v1, v0, s[10:11] sc1
	s_mov_b64 s[24:25], 0
	s_waitcnt vmcnt(0)
	v_cmp_eq_u32_e32 vcc, v1, v2
	s_and_saveexec_b64 s[22:23], vcc
	s_cbranch_execz .LBB0_810
	s_add_u32 s18, s30, 0x4a0200
	s_addc_u32 s19, s31, 0
	s_mov_b32 s44, 1
	s_branch .LBB0_803

.LBB0_811:
	s_or_b64 exec, exec, s[8:9]
	s_and_saveexec_b64 s[8:9], s[18:19]
	s_cbranch_execz .LBB0_813
	v_mov_b32_e32 v2, 1
	global_atomic_add v[0:1], v2, off
	buffer_inv sc1
.LBB0_813:
	s_or_b64 exec, exec, s[8:9]
	s_mov_b64 s[8:9], exec
	v_mbcnt_lo_u32_b32 v0, s8, 0
	v_mbcnt_hi_u32_b32 v0, s9, v0
	v_cmp_eq_u32_e32 vcc, 0, v0
	s_waitcnt vmcnt(0)
	s_and_saveexec_b64 s[10:11], vcc
	s_cbranch_execz .LBB0_815
	s_bcnt1_i32_b64 s8, s[8:9]
	v_mov_b32_e32 v0, 0x2000
	v_mov_b32_e32 v1, s8
	global_atomic_add v0, v1, s[6:7] offset:1024

.LBB0_1012:
	s_or_b64 exec, exec, s[10:11]
	v_cvt_f32_u32_e32 v4, v2
	s_waitcnt vmcnt(0)
	v_readfirstlane_b32 s8, v3
	v_sub_u32_e32 v3, 0, v2
	v_rcp_iflag_f32_e32 v4, v4
	v_add_u32_e32 v5, s8, v1
	v_mul_f32_e32 v4, 0x4f7ffffe, v4
	v_cvt_u32_f32_e32 v4, v4
	v_mul_lo_u32 v1, v3, v4
	v_mul_hi_u32 v1, v4, v1
	v_add_u32_e32 v1, v4, v1
	v_mul_hi_u32 v1, v5, v1
	v_mul_lo_u32 v3, v1, v2
	v_sub_u32_e32 v3, v5, v3
	v_add_u32_e32 v4, 1, v1
	v_cmp_ge_u32_e32 vcc, v3, v2
	s_nop 1
	v_cndmask_b32_e32 v1, v1, v4, vcc
	v_sub_u32_e32 v4, v3, v2
	v_cndmask_b32_e32 v3, v3, v4, vcc
	v_add_u32_e32 v4, 1, v1
	v_cmp_ge_u32_e32 vcc, v3, v2
	v_add_u32_e32 v3, 1, v5
	s_nop 0
	v_cndmask_b32_e32 v1, v1, v4, vcc
	v_mul_lo_u32 v4, v2, v1
	v_add_u32_e32 v2, v4, v2
	v_cmp_ne_u32_e32 vcc, v3, v2
	s_and_saveexec_b64 s[8:9], vcc
	s_xor_b64 s[8:9], exec, s[8:9]
	s_cbranch_execz .LBB0_1026
	s_waitcnt lgkmcnt(0)
	buffer_inv sc1
	v_mov_b32_e32 v0, 0x2000
	global_load_dword v0, v0, s[6:7] offset:1024 sc1
	s_add_u32 s18, s6, 0x2400
	s_addc_u32 s19, s7, 0
	s_waitcnt vmcnt(0)
	v_cmp_eq_u32_e32 vcc, v0, v1
	s_and_saveexec_b64 s[10:11], vcc
	s_cbranch_execz .LBB0_1025
	s_add_u32 s14, s30, 0x4a0200
	s_addc_u32 s15, s31, 0
	s_mov_b32 s40, 1
	s_mov_b64 s[22:23], 0
	v_mov_b32_e32 v0, 0
	s_branch .LBB0_1016

.LBB0_1029:
	s_or_b64 exec, exec, s[10:11]
	v_cvt_f32_u32_e32 v3, v0
	s_waitcnt vmcnt(0)
	v_readfirstlane_b32 s8, v2
	s_add_u32 s10, s30, 0x4a3500
	s_addc_u32 s11, s31, 0
	v_rcp_iflag_f32_e32 v3, v3
	v_add_u32_e32 v1, s8, v1
	v_add_u32_e32 v4, 1, v1
	s_mov_b64 s[14:15], -1
	v_mul_f32_e32 v2, 0x4f7ffffe, v3
	v_cvt_u32_f32_e32 v2, v2
	v_sub_u32_e32 v3, 0, v0
	v_mul_lo_u32 v3, v3, v2
	v_mul_hi_u32 v3, v2, v3
	v_add_u32_e32 v2, v2, v3
	v_mul_hi_u32 v2, v1, v2
	v_mul_lo_u32 v3, v2, v0
	v_sub_u32_e32 v1, v1, v3
	v_add_u32_e32 v5, 1, v2
	v_cmp_ge_u32_e32 vcc, v1, v0
	v_sub_u32_e32 v3, v1, v0
	s_nop 0
	v_cndmask_b32_e32 v2, v2, v5, vcc
	v_cndmask_b32_e32 v1, v1, v3, vcc
	v_add_u32_e32 v3, 1, v2
	v_cmp_ge_u32_e32 vcc, v1, v0
	s_nop 1
	v_cndmask_b32_e32 v2, v2, v3, vcc
	v_mul_lo_u32 v1, v0, v2
	v_add_u32_e32 v0, v1, v0
	v_cmp_ne_u32_e32 vcc, v4, v0
	v_mov_b64_e32 v[0:1], s[10:11]
	s_and_saveexec_b64 s[8:9], vcc
	s_cbranch_execz .LBB0_1041
	buffer_inv sc1
	v_mov_b32_e32 v0, 0
	global_load_dword v1, v0, s[10:11] sc1
	s_mov_b64 s[22:23], 0
	s_waitcnt vmcnt(0)
	v_cmp_eq_u32_e32 vcc, v1, v2
	s_and_saveexec_b64 s[18:19], vcc
	s_cbranch_execz .LBB0_1040
	s_add_u32 s14, s30, 0x4a0200
	s_addc_u32 s15, s31, 0
	s_mov_b32 s38, 1
	s_branch .LBB0_1033

.LBB0_1041:
	s_or_b64 exec, exec, s[8:9]
	s_and_saveexec_b64 s[8:9], s[14:15]
	s_cbranch_execz .LBB0_1043
	v_mov_b32_e32 v2, 1
	global_atomic_add v[0:1], v2, off
	buffer_inv sc1

.LBB0_1070:
	s_and_b64 vcc, exec, s[0:1]
	s_mov_b64 s[0:1], -1
	v_mbcnt_lo_u32_b32 v144, -1, 0
	v_mbcnt_hi_u32_b32 v144, -1, v144
	s_lshr_b32 s60, s33, 12
	s_lshl_b32 s61, s53, 2
	s_add_i32 s60, s60, s61
	s_lshr_b32 s61, s33, 10
	s_and_b32 s61, s61, 3
	s_lshl_b32 s62, s60, 18
	s_lshl_b32 s60, s60, 17
	s_lshl_b32 s63, s54, 9
	s_add_i32 s60, s60, s63
	s_lshl_b32 s63, s54, 10
	s_add_i32 s62, s62, s63
	s_lshl_b32 s63, s61, 6
	s_add_i32 s60, s60, s63
	s_lshl_b32 s63, s61, 7
	s_add_i32 s62, s62, s63
	s_lshr_b32 s61, s33, 10
	s_mulk_i32 s61, 0x500
	s_add_i32 s61, s61, 0x20400
	v_lshrrev_b32_e32 v140, 2, v144
	v_and_b32_e32 v145, 3, v144
	v_mul_u32_u24_e32 v141, 0x50, v140
	v_lshl_add_u32 v141, v145, 4, v141
	v_add_u32_e32 v141, s61, v141
	v_lshlrev_b32_e32 v143, 12, v140
	v_lshl_add_u32 v143, v145, 4, v143
	v_add_u32_e32 v143, s62, v143
	v_lshlrev_b32_e32 v140, 11, v140
	v_lshl_add_u32 v140, v145, 4, v140
	v_add_u32_e32 v140, s60, v140
	v_and_b32_e32 v145, 15, v144
	v_lshrrev_b32_e32 v144, 4, v144
	v_mul_u32_u24_e32 v142, 0x50, v145
	v_add_u32_e32 v142, s61, v142
	v_lshl_add_u32 v152, v144, 4, v142
	v_lshl_add_u32 v142, v144, 3, v142
	global_load_dwordx4 v[160:163], v140, s[12:13]
	global_load_dwordx4 v[164:167], v140, s[12:13] offset:256
	v_add_u32_e32 v144, 0x8000, v140
	global_load_dwordx4 v[168:171], v144, s[12:13]
	global_load_dwordx4 v[172:175], v144, s[12:13] offset:256
	v_add_u32_e32 v144, 0x10000, v140
	global_load_dwordx4 v[176:179], v144, s[12:13]
	global_load_dwordx4 v[180:183], v144, s[12:13] offset:256
	v_add_u32_e32 v144, 0x18000, v140
	global_load_dwordx4 v[184:187], v144, s[12:13]
	global_load_dwordx4 v[188:191], v144, s[12:13] offset:256
	v_add_u32_e32 v144, 0x40000, v140
	global_load_dwordx4 v[192:195], v144, s[12:13]
	global_load_dwordx4 v[196:199], v144, s[12:13] offset:256
	v_add_u32_e32 v144, 0x48000, v140
	global_load_dwordx4 v[200:203], v144, s[12:13]
	global_load_dwordx4 v[204:207], v144, s[12:13] offset:256
	v_add_u32_e32 v144, 0x50000, v140
	global_load_dwordx4 v[208:211], v144, s[12:13]
	global_load_dwordx4 v[212:215], v144, s[12:13] offset:256
	v_add_u32_e32 v144, 0x58000, v140
	global_load_dwordx4 v[216:219], v144, s[12:13]
	global_load_dwordx4 v[220:223], v144, s[12:13] offset:256
	s_waitcnt vmcnt(15)
	ds_write_b128 v141, v[160:163]
	ds_read2_b64 v[232:235], v142 offset1:4
	s_waitcnt lgkmcnt(0)
	v_lshlrev_b32_e32 v224, 16, v232
	v_and_b32_e32 v225, 0xffff0000, v232
	v_lshlrev_b32_e32 v226, 16, v233
	v_and_b32_e32 v227, 0xffff0000, v233
	v_pk_add_f32 v[124:125], v[124:125], v[224:225]
	v_pk_add_f32 v[126:127], v[126:127], v[226:227]
	v_lshlrev_b32_e32 v228, 16, v234
	v_and_b32_e32 v229, 0xffff0000, v234
	v_lshlrev_b32_e32 v230, 16, v235
	v_and_b32_e32 v231, 0xffff0000, v235
	v_pk_add_f32 v[120:121], v[120:121], v[228:229]
	v_pk_add_f32 v[122:123], v[122:123], v[230:231]
	ds_write_b128 v152, v[124:127]
	ds_read_b128 v[236:239], v141
	s_waitcnt lgkmcnt(0)
	global_store_dwordx4 v143, v[236:239], s[28:29]
	ds_write_b128 v152, v[120:123]
	ds_read_b128 v[240:243], v141
	s_waitcnt lgkmcnt(0)
	global_store_dwordx4 v143, v[240:243], s[28:29] offset:64
	s_waitcnt vmcnt(16)
	ds_write_b128 v141, v[164:167]
	ds_read2_b64 v[232:235], v142 offset1:4
	s_waitcnt lgkmcnt(0)
	v_lshlrev_b32_e32 v224, 16, v232
	v_and_b32_e32 v225, 0xffff0000, v232
	v_lshlrev_b32_e32 v226, 16, v233
	v_and_b32_e32 v227, 0xffff0000, v233
	v_pk_add_f32 v[116:117], v[116:117], v[224:225]
	v_pk_add_f32 v[118:119], v[118:119], v[226:227]
	v_lshlrev_b32_e32 v228, 16, v234
	v_and_b32_e32 v229, 0xffff0000, v234
	v_lshlrev_b32_e32 v230, 16, v235
	v_and_b32_e32 v231, 0xffff0000, v235
	v_pk_add_f32 v[108:109], v[108:109], v[228:229]
	v_pk_add_f32 v[110:111], v[110:111], v[230:231]
	ds_write_b128 v152, v[116:119]
	ds_read_b128 v[236:239], v141
	s_waitcnt lgkmcnt(0)
	global_store_dwordx4 v143, v[236:239], s[28:29] offset:512
	ds_write_b128 v152, v[108:111]
	ds_read_b128 v[240:243], v141
	s_waitcnt lgkmcnt(0)
	global_store_dwordx4 v143, v[240:243], s[28:29] offset:576
	v_add_u32_e32 v144, 0x10000, v143
	s_waitcnt vmcnt(17)
	ds_write_b128 v141, v[168:171]
	ds_read2_b64 v[232:235], v142 offset1:4
	s_waitcnt lgkmcnt(0)
	v_lshlrev_b32_e32 v224, 16, v232
	v_and_b32_e32 v225, 0xffff0000, v232
	v_lshlrev_b32_e32 v226, 16, v233
	v_and_b32_e32 v227, 0xffff0000, v233
	v_pk_add_f32 v[112:113], v[112:113], v[224:225]
	v_pk_add_f32 v[114:115], v[114:115], v[226:227]
	v_lshlrev_b32_e32 v228, 16, v234
	v_and_b32_e32 v229, 0xffff0000, v234
	v_lshlrev_b32_e32 v230, 16, v235
	v_and_b32_e32 v231, 0xffff0000, v235
	v_pk_add_f32 v[104:105], v[104:105], v[228:229]
	v_pk_add_f32 v[106:107], v[106:107], v[230:231]
	ds_write_b128 v152, v[112:115]
	ds_read_b128 v[236:239], v141
	s_waitcnt lgkmcnt(0)
	global_store_dwordx4 v144, v[236:239], s[28:29]
	ds_write_b128 v152, v[104:107]
	ds_read_b128 v[240:243], v141
	s_waitcnt lgkmcnt(0)
	global_store_dwordx4 v144, v[240:243], s[28:29] offset:64
	s_waitcnt vmcnt(18)
	ds_write_b128 v141, v[172:175]
	ds_read2_b64 v[232:235], v142 offset1:4
	s_waitcnt lgkmcnt(0)
	v_lshlrev_b32_e32 v224, 16, v232
	v_and_b32_e32 v225, 0xffff0000, v232
	v_lshlrev_b32_e32 v226, 16, v233
	v_and_b32_e32 v227, 0xffff0000, v233
	v_pk_add_f32 v[100:101], v[100:101], v[224:225]
	v_pk_add_f32 v[102:103], v[102:103], v[226:227]
	v_lshlrev_b32_e32 v228, 16, v234
	v_and_b32_e32 v229, 0xffff0000, v234
	v_lshlrev_b32_e32 v230, 16, v235
	v_and_b32_e32 v231, 0xffff0000, v235
	v_pk_add_f32 v[92:93], v[92:93], v[228:229]
	v_pk_add_f32 v[94:95], v[94:95], v[230:231]
	ds_write_b128 v152, v[100:103]
	ds_read_b128 v[236:239], v141
	s_waitcnt lgkmcnt(0)
	global_store_dwordx4 v144, v[236:239], s[28:29] offset:512
	ds_write_b128 v152, v[92:95]
	ds_read_b128 v[240:243], v141
	s_waitcnt lgkmcnt(0)
	global_store_dwordx4 v144, v[240:243], s[28:29] offset:576
	v_add_u32_e32 v144, 0x20000, v143
	s_waitcnt vmcnt(19)
	ds_write_b128 v141, v[176:179]
	ds_read2_b64 v[232:235], v142 offset1:4
	s_waitcnt lgkmcnt(0)
	v_lshlrev_b32_e32 v224, 16, v232
	v_and_b32_e32 v225, 0xffff0000, v232
	v_lshlrev_b32_e32 v226, 16, v233
	v_and_b32_e32 v227, 0xffff0000, v233
	v_pk_add_f32 v[96:97], v[96:97], v[224:225]
	v_pk_add_f32 v[98:99], v[98:99], v[226:227]
	v_lshlrev_b32_e32 v228, 16, v234
	v_and_b32_e32 v229, 0xffff0000, v234
	v_lshlrev_b32_e32 v230, 16, v235
	v_and_b32_e32 v231, 0xffff0000, v235
	v_pk_add_f32 v[88:89], v[88:89], v[228:229]
	v_pk_add_f32 v[90:91], v[90:91], v[230:231]
	ds_write_b128 v152, v[96:99]
	ds_read_b128 v[236:239], v141
	s_waitcnt lgkmcnt(0)
	global_store_dwordx4 v144, v[236:239], s[28:29]
	ds_write_b128 v152, v[88:91]
	ds_read_b128 v[240:243], v141
	s_waitcnt lgkmcnt(0)
	global_store_dwordx4 v144, v[240:243], s[28:29] offset:64
	s_waitcnt vmcnt(20)
	ds_write_b128 v141, v[180:183]
	ds_read2_b64 v[232:235], v142 offset1:4
	s_waitcnt lgkmcnt(0)
	v_lshlrev_b32_e32 v224, 16, v232
	v_and_b32_e32 v225, 0xffff0000, v232
	v_lshlrev_b32_e32 v226, 16, v233
	v_and_b32_e32 v227, 0xffff0000, v233
	v_pk_add_f32 v[84:85], v[84:85], v[224:225]
	v_pk_add_f32 v[86:87], v[86:87], v[226:227]
	v_lshlrev_b32_e32 v228, 16, v234
	v_and_b32_e32 v229, 0xffff0000, v234
	v_lshlrev_b32_e32 v230, 16, v235
	v_and_b32_e32 v231, 0xffff0000, v235
	v_pk_add_f32 v[76:77], v[76:77], v[228:229]
	v_pk_add_f32 v[78:79], v[78:79], v[230:231]
	ds_write_b128 v152, v[84:87]
	ds_read_b128 v[236:239], v141
	s_waitcnt lgkmcnt(0)
	global_store_dwordx4 v144, v[236:239], s[28:29] offset:512
	ds_write_b128 v152, v[76:79]
	ds_read_b128 v[240:243], v141
	s_waitcnt lgkmcnt(0)
	global_store_dwordx4 v144, v[240:243], s[28:29] offset:576
	v_add_u32_e32 v144, 0x30000, v143
	s_waitcnt vmcnt(21)
	ds_write_b128 v141, v[184:187]
	ds_read2_b64 v[232:235], v142 offset1:4
	s_waitcnt lgkmcnt(0)
	v_lshlrev_b32_e32 v224, 16, v232
	v_and_b32_e32 v225, 0xffff0000, v232
	v_lshlrev_b32_e32 v226, 16, v233
	v_and_b32_e32 v227, 0xffff0000, v233
	v_pk_add_f32 v[80:81], v[80:81], v[224:225]
	v_pk_add_f32 v[82:83], v[82:83], v[226:227]
	v_lshlrev_b32_e32 v228, 16, v234
	v_and_b32_e32 v229, 0xffff0000, v234
	v_lshlrev_b32_e32 v230, 16, v235
	v_and_b32_e32 v231, 0xffff0000, v235
	v_pk_add_f32 v[72:73], v[72:73], v[228:229]
	v_pk_add_f32 v[74:75], v[74:75], v[230:231]
	ds_write_b128 v152, v[80:83]
	ds_read_b128 v[236:239], v141
	s_waitcnt lgkmcnt(0)
	global_store_dwordx4 v144, v[236:239], s[28:29]
	ds_write_b128 v152, v[72:75]
	ds_read_b128 v[240:243], v141
	s_waitcnt lgkmcnt(0)
	global_store_dwordx4 v144, v[240:243], s[28:29] offset:64
	s_waitcnt vmcnt(22)
	ds_write_b128 v141, v[188:191]
	ds_read2_b64 v[232:235], v142 offset1:4
	s_waitcnt lgkmcnt(0)
	v_lshlrev_b32_e32 v224, 16, v232
	v_and_b32_e32 v225, 0xffff0000, v232
	v_lshlrev_b32_e32 v226, 16, v233
	v_and_b32_e32 v227, 0xffff0000, v233
	v_pk_add_f32 v[68:69], v[68:69], v[224:225]
	v_pk_add_f32 v[70:71], v[70:71], v[226:227]
	v_lshlrev_b32_e32 v228, 16, v234
	v_and_b32_e32 v229, 0xffff0000, v234
	v_lshlrev_b32_e32 v230, 16, v235
	v_and_b32_e32 v231, 0xffff0000, v235
	v_pk_add_f32 v[64:65], v[64:65], v[228:229]
	v_pk_add_f32 v[66:67], v[66:67], v[230:231]
	ds_write_b128 v152, v[68:71]
	ds_read_b128 v[236:239], v141
	s_waitcnt lgkmcnt(0)
	global_store_dwordx4 v144, v[236:239], s[28:29] offset:512
	ds_write_b128 v152, v[64:67]
	ds_read_b128 v[240:243], v141
	s_waitcnt lgkmcnt(0)
	global_store_dwordx4 v144, v[240:243], s[28:29] offset:576
	v_add_u32_e32 v144, 0x80000, v143
	s_waitcnt vmcnt(23)
	ds_write_b128 v141, v[192:195]
	ds_read2_b64 v[232:235], v142 offset1:4
	s_waitcnt lgkmcnt(0)
	v_lshlrev_b32_e32 v224, 16, v232
	v_and_b32_e32 v225, 0xffff0000, v232
	v_lshlrev_b32_e32 v226, 16, v233
	v_and_b32_e32 v227, 0xffff0000, v233
	v_pk_add_f32 v[60:61], v[60:61], v[224:225]
	v_pk_add_f32 v[62:63], v[62:63], v[226:227]
	v_lshlrev_b32_e32 v228, 16, v234
	v_and_b32_e32 v229, 0xffff0000, v234
	v_lshlrev_b32_e32 v230, 16, v235
	v_and_b32_e32 v231, 0xffff0000, v235
	v_pk_add_f32 v[56:57], v[56:57], v[228:229]
	v_pk_add_f32 v[58:59], v[58:59], v[230:231]
	ds_write_b128 v152, v[60:63]
	ds_read_b128 v[236:239], v141
	s_waitcnt lgkmcnt(0)
	global_store_dwordx4 v144, v[236:239], s[28:29]
	ds_write_b128 v152, v[56:59]
	ds_read_b128 v[240:243], v141
	s_waitcnt lgkmcnt(0)
	global_store_dwordx4 v144, v[240:243], s[28:29] offset:64
	s_waitcnt vmcnt(24)
	ds_write_b128 v141, v[196:199]
	ds_read2_b64 v[232:235], v142 offset1:4
	s_waitcnt lgkmcnt(0)
	v_lshlrev_b32_e32 v224, 16, v232
	v_and_b32_e32 v225, 0xffff0000, v232
	v_lshlrev_b32_e32 v226, 16, v233
	v_and_b32_e32 v227, 0xffff0000, v233
	v_pk_add_f32 v[52:53], v[52:53], v[224:225]
	v_pk_add_f32 v[54:55], v[54:55], v[226:227]
	v_lshlrev_b32_e32 v228, 16, v234
	v_and_b32_e32 v229, 0xffff0000, v234
	v_lshlrev_b32_e32 v230, 16, v235
	v_and_b32_e32 v231, 0xffff0000, v235
	v_pk_add_f32 v[44:45], v[44:45], v[228:229]
	v_pk_add_f32 v[46:47], v[46:47], v[230:231]
	ds_write_b128 v152, v[52:55]
	ds_read_b128 v[236:239], v141
	s_waitcnt lgkmcnt(0)
	global_store_dwordx4 v144, v[236:239], s[28:29] offset:512
	ds_write_b128 v152, v[44:47]
	ds_read_b128 v[240:243], v141
	s_waitcnt lgkmcnt(0)
	global_store_dwordx4 v144, v[240:243], s[28:29] offset:576
	v_add_u32_e32 v144, 0x90000, v143
	s_waitcnt vmcnt(25)
	ds_write_b128 v141, v[200:203]
	ds_read2_b64 v[232:235], v142 offset1:4
	s_waitcnt lgkmcnt(0)
	v_lshlrev_b32_e32 v224, 16, v232
	v_and_b32_e32 v225, 0xffff0000, v232
	v_lshlrev_b32_e32 v226, 16, v233
	v_and_b32_e32 v227, 0xffff0000, v233
	v_pk_add_f32 v[48:49], v[48:49], v[224:225]
	v_pk_add_f32 v[50:51], v[50:51], v[226:227]
	v_lshlrev_b32_e32 v228, 16, v234
	v_and_b32_e32 v229, 0xffff0000, v234
	v_lshlrev_b32_e32 v230, 16, v235
	v_and_b32_e32 v231, 0xffff0000, v235
	v_pk_add_f32 v[40:41], v[40:41], v[228:229]
	v_pk_add_f32 v[42:43], v[42:43], v[230:231]
	ds_write_b128 v152, v[48:51]
	ds_read_b128 v[236:239], v141
	s_waitcnt lgkmcnt(0)
	global_store_dwordx4 v144, v[236:239], s[28:29]
	ds_write_b128 v152, v[40:43]
	ds_read_b128 v[240:243], v141
	s_waitcnt lgkmcnt(0)
	global_store_dwordx4 v144, v[240:243], s[28:29] offset:64
	s_waitcnt vmcnt(26)
	ds_write_b128 v141, v[204:207]
	ds_read2_b64 v[232:235], v142 offset1:4
	s_waitcnt lgkmcnt(0)
	v_lshlrev_b32_e32 v224, 16, v232
	v_and_b32_e32 v225, 0xffff0000, v232
	v_lshlrev_b32_e32 v226, 16, v233
	v_and_b32_e32 v227, 0xffff0000, v233
	v_pk_add_f32 v[36:37], v[36:37], v[224:225]
	v_pk_add_f32 v[38:39], v[38:39], v[226:227]
	v_lshlrev_b32_e32 v228, 16, v234
	v_and_b32_e32 v229, 0xffff0000, v234
	v_lshlrev_b32_e32 v230, 16, v235
	v_and_b32_e32 v231, 0xffff0000, v235
	v_pk_add_f32 v[28:29], v[28:29], v[228:229]
	v_pk_add_f32 v[30:31], v[30:31], v[230:231]
	ds_write_b128 v152, v[36:39]
	ds_read_b128 v[236:239], v141
	s_waitcnt lgkmcnt(0)
	global_store_dwordx4 v144, v[236:239], s[28:29] offset:512
	ds_write_b128 v152, v[28:31]
	ds_read_b128 v[240:243], v141
	s_waitcnt lgkmcnt(0)
	global_store_dwordx4 v144, v[240:243], s[28:29] offset:576
	v_add_u32_e32 v144, 0xa0000, v143
	s_waitcnt vmcnt(27)
	ds_write_b128 v141, v[208:211]
	ds_read2_b64 v[232:235], v142 offset1:4
	s_waitcnt lgkmcnt(0)
	v_lshlrev_b32_e32 v224, 16, v232
	v_and_b32_e32 v225, 0xffff0000, v232
	v_lshlrev_b32_e32 v226, 16, v233
	v_and_b32_e32 v227, 0xffff0000, v233
	v_pk_add_f32 v[32:33], v[32:33], v[224:225]
	v_pk_add_f32 v[34:35], v[34:35], v[226:227]
	v_lshlrev_b32_e32 v228, 16, v234
	v_and_b32_e32 v229, 0xffff0000, v234
	v_lshlrev_b32_e32 v230, 16, v235
	v_and_b32_e32 v231, 0xffff0000, v235
	v_pk_add_f32 v[24:25], v[24:25], v[228:229]
	v_pk_add_f32 v[26:27], v[26:27], v[230:231]
	ds_write_b128 v152, v[32:35]
	ds_read_b128 v[236:239], v141
	s_waitcnt lgkmcnt(0)
	global_store_dwordx4 v144, v[236:239], s[28:29]
	ds_write_b128 v152, v[24:27]
	ds_read_b128 v[240:243], v141
	s_waitcnt lgkmcnt(0)
	global_store_dwordx4 v144, v[240:243], s[28:29] offset:64
	s_waitcnt vmcnt(28)
	ds_write_b128 v141, v[212:215]
	ds_read2_b64 v[232:235], v142 offset1:4
	s_waitcnt lgkmcnt(0)
	v_lshlrev_b32_e32 v224, 16, v232
	v_and_b32_e32 v225, 0xffff0000, v232
	v_lshlrev_b32_e32 v226, 16, v233
	v_and_b32_e32 v227, 0xffff0000, v233
	v_pk_add_f32 v[20:21], v[20:21], v[224:225]
	v_pk_add_f32 v[22:23], v[22:23], v[226:227]
	v_lshlrev_b32_e32 v228, 16, v234
	v_and_b32_e32 v229, 0xffff0000, v234
	v_lshlrev_b32_e32 v230, 16, v235
	v_and_b32_e32 v231, 0xffff0000, v235
	v_pk_add_f32 v[12:13], v[12:13], v[228:229]
	v_pk_add_f32 v[14:15], v[14:15], v[230:231]
	ds_write_b128 v152, v[20:23]
	ds_read_b128 v[236:239], v141
	s_waitcnt lgkmcnt(0)
	global_store_dwordx4 v144, v[236:239], s[28:29] offset:512
	ds_write_b128 v152, v[12:15]
	ds_read_b128 v[240:243], v141
	s_waitcnt lgkmcnt(0)
	global_store_dwordx4 v144, v[240:243], s[28:29] offset:576
	v_add_u32_e32 v144, 0xb0000, v143
	s_waitcnt vmcnt(29)
	ds_write_b128 v141, v[216:219]
	ds_read2_b64 v[232:235], v142 offset1:4
	s_waitcnt lgkmcnt(0)
	v_lshlrev_b32_e32 v224, 16, v232
	v_and_b32_e32 v225, 0xffff0000, v232
	v_lshlrev_b32_e32 v226, 16, v233
	v_and_b32_e32 v227, 0xffff0000, v233
	v_pk_add_f32 v[16:17], v[16:17], v[224:225]
	v_pk_add_f32 v[18:19], v[18:19], v[226:227]
	v_lshlrev_b32_e32 v228, 16, v234
	v_and_b32_e32 v229, 0xffff0000, v234
	v_lshlrev_b32_e32 v230, 16, v235
	v_and_b32_e32 v231, 0xffff0000, v235
	v_pk_add_f32 v[8:9], v[8:9], v[228:229]
	v_pk_add_f32 v[10:11], v[10:11], v[230:231]
	ds_write_b128 v152, v[16:19]
	ds_read_b128 v[236:239], v141
	s_waitcnt lgkmcnt(0)
	global_store_dwordx4 v144, v[236:239], s[28:29]
	ds_write_b128 v152, v[8:11]
	ds_read_b128 v[240:243], v141
	s_waitcnt lgkmcnt(0)
	global_store_dwordx4 v144, v[240:243], s[28:29] offset:64
	s_waitcnt vmcnt(30)
	ds_write_b128 v141, v[220:223]
	ds_read2_b64 v[232:235], v142 offset1:4
	s_waitcnt lgkmcnt(0)
	v_lshlrev_b32_e32 v224, 16, v232
	v_and_b32_e32 v225, 0xffff0000, v232
	v_lshlrev_b32_e32 v226, 16, v233
	v_and_b32_e32 v227, 0xffff0000, v233
	v_pk_add_f32 v[4:5], v[4:5], v[224:225]
	v_pk_add_f32 v[6:7], v[6:7], v[226:227]
	v_lshlrev_b32_e32 v228, 16, v234
	v_and_b32_e32 v229, 0xffff0000, v234
	v_lshlrev_b32_e32 v230, 16, v235
	v_and_b32_e32 v231, 0xffff0000, v235
	v_pk_add_f32 v[0:1], v[0:1], v[228:229]
	v_pk_add_f32 v[2:3], v[2:3], v[230:231]
	ds_write_b128 v152, v[4:7]
	ds_read_b128 v[236:239], v141
	s_waitcnt lgkmcnt(0)
	global_store_dwordx4 v144, v[236:239], s[28:29] offset:512
	ds_write_b128 v152, v[0:3]
	ds_read_b128 v[240:243], v141
	s_waitcnt lgkmcnt(0)
	global_store_dwordx4 v144, v[240:243], s[28:29] offset:576
	s_cbranch_vccnz .LBB0_1055
	s_andn2_b64 vcc, exec, s[6:7]
	s_cbranch_vccnz .LBB0_1054
	s_barrier
	s_branch .LBB0_1054
